# grid barrier: non-leader workgroups issue the L1 invalidate when they start spinning (nothing but barrier words is read until the release) instead of after the release
# baseline (speedup 1.0000x reference)
; #define LAS __attribute__((address_space(3)))
; __device__ __forceinline__ int otid(int wv0) { int t = (wv0 << 6) | olane(); asm volatile("" : "+v"(t)); return t; }
; __device__ __forceinline__ unsigned xb_ld(unsigned* p)              { return __hip_atomic_load(p, __ATOMIC_RELAXED, __HIP_MEMORY_SCOPE_AGENT); }
; __device__ __forceinline__ unsigned xb_add(unsigned* p, unsigned v) { return __hip_atomic_fetch_add(p, v, __ATOMIC_RELAXED, __HIP_MEMORY_SCOPE_AGENT); }
; __device__ __forceinline__ unsigned xb_xcc_id() { return (unsigned)__builtin_amdgcn_s_getreg((3 << 11) | 20) & 0xFu; }
; #define XB_SPIN(cond, bar) do { unsigned _sp = 0; while (cond) { __builtin_amdgcn_s_sleep(1); \
;     if ((++_sp & 255u) == 0u) { if (xb_ld(&(bar)[XB_TMO])) break; if (_sp > XB_SPIN_CAP) { atomicAdd(&(bar)[XB_TMO], 1u); break; } } } } while (0)
; __device__ __forceinline__ void xcd_barrier(unsigned* bar, volatile LAS unsigned* st, int wv0) {
;     asm volatile("s_waitcnt vmcnt(0)" ::: "memory");
;     __syncthreads();
;     if (otid(wv0) == 0) {
;         const unsigned x = xb_xcc_id();
;         __builtin_amdgcn_s_waitcnt(0);
;         unsigned nloc = st[0], nx = st[1];
;         if (nloc == 0u) { xcd_barrier_complete(bar, x, nloc, nx); st[0] = nloc; st[1] = nx; }
;         const unsigned old = xb_add(&bar[XB_XSUB(x)], 1u);
;         const unsigned gen = old / nloc;
;         if (old + 1u == (gen + 1u) * nloc) {
;             __builtin_amdgcn_fence(__ATOMIC_RELEASE, "agent");
;             asm volatile("s_waitcnt vmcnt(0)" ::: "memory");
;             const unsigned og = xb_add(&bar[XB_TOP], 1u);
;             const unsigned tg = og / nx;
;             if (og + 1u == (tg + 1u) * nx) xb_add(&bar[XB_TOPGEN], 1u);
;             else XB_SPIN(xb_ld(&bar[XB_TOPGEN]) == tg, bar);
;             __builtin_amdgcn_fence(__ATOMIC_ACQUIRE, "agent");
;             xb_add(&bar[XB_XGEN(x)], 1u);
;             asm volatile("s_waitcnt vmcnt(0)" ::: "memory");
;         } else {
;             XB_SPIN(xb_ld(&bar[XB_XGEN(x)]) == gen, bar);
;             __builtin_amdgcn_fence(__ATOMIC_ACQUIRE, "agent");
;             asm volatile("s_waitcnt vmcnt(0)" ::: "memory");
.LBB0_536:
	s_or_b64 exec, exec, s[8:9]
	v_cvt_f32_u32_e32 v4, v2
	s_waitcnt vmcnt(0)
	v_readfirstlane_b32 s0, v3
	v_sub_u32_e32 v3, 0, v2
	v_rcp_iflag_f32_e32 v4, v4
	v_add_u32_e32 v5, s0, v1
	v_mul_f32_e32 v4, 0x4f7ffffe, v4
	v_cvt_u32_f32_e32 v4, v4
	v_mul_lo_u32 v1, v3, v4
	v_mul_hi_u32 v1, v4, v1
	v_add_u32_e32 v1, v4, v1
	v_mul_hi_u32 v1, v5, v1
	v_mul_lo_u32 v3, v1, v2
	v_sub_u32_e32 v3, v5, v3
	v_add_u32_e32 v4, 1, v1
	v_cmp_ge_u32_e32 vcc, v3, v2
	s_nop 1
	v_cndmask_b32_e32 v1, v1, v4, vcc
	v_sub_u32_e32 v4, v3, v2
	v_cndmask_b32_e32 v3, v3, v4, vcc
	v_add_u32_e32 v4, 1, v1
	v_cmp_ge_u32_e32 vcc, v3, v2
	v_add_u32_e32 v3, 1, v5
	s_nop 0
	v_cndmask_b32_e32 v1, v1, v4, vcc
	v_mul_lo_u32 v4, v2, v1
	v_add_u32_e32 v2, v4, v2
	v_cmp_ne_u32_e32 vcc, v3, v2
	s_and_saveexec_b64 s[0:1], vcc
	s_xor_b64 s[6:7], exec, s[0:1]
	s_cbranch_execz .LBB0_550
	buffer_inv sc1
	s_waitcnt lgkmcnt(0)
	global_load_dword v0, v231, s[4:5] offset:1024 sc1
	s_add_u32 s14, s4, 0x2400
	s_addc_u32 s15, s5, 0
	s_waitcnt vmcnt(0)
	v_cmp_eq_u32_e32 vcc, v0, v1
	s_and_saveexec_b64 s[8:9], vcc
	s_cbranch_execz .LBB0_549
	s_add_u32 s12, s10, 0x27740200
	s_addc_u32 s13, s11, 0
	s_mov_b32 s0, 1
	s_mov_b64 s[16:17], 0
	s_branch .LBB0_540

; __device__ __forceinline__ unsigned xb_ld(unsigned* p)              { return __hip_atomic_load(p, __ATOMIC_RELAXED, __HIP_MEMORY_SCOPE_AGENT); }
; #define XB_SPIN(cond, bar) do { unsigned _sp = 0; while (cond) { __builtin_amdgcn_s_sleep(1); \
;     if ((++_sp & 255u) == 0u) { if (xb_ld(&(bar)[XB_TMO])) break; if (_sp > XB_SPIN_CAP) { atomicAdd(&(bar)[XB_TMO], 1u); break; } } } } while (0)
; __device__ __forceinline__ void xcd_barrier(unsigned* bar, volatile LAS unsigned* st, int wv0) {
;     ...
;             XB_SPIN(xb_ld(&bar[XB_XGEN(x)]) == gen, bar);
;             __builtin_amdgcn_fence(__ATOMIC_ACQUIRE, "agent");
;             asm volatile("s_waitcnt vmcnt(0)" ::: "memory");
.LBB0_549:
	s_or_b64 exec, exec, s[8:9]
	s_waitcnt vmcnt(0)
	s_waitcnt vmcnt(0)

; __device__ __forceinline__ unsigned xb_ld(unsigned* p)              { return __hip_atomic_load(p, __ATOMIC_RELAXED, __HIP_MEMORY_SCOPE_AGENT); }
; __device__ __forceinline__ unsigned xb_add(unsigned* p, unsigned v) { return __hip_atomic_fetch_add(p, v, __ATOMIC_RELAXED, __HIP_MEMORY_SCOPE_AGENT); }
; #define XB_SPIN(cond, bar) do { unsigned _sp = 0; while (cond) { __builtin_amdgcn_s_sleep(1); \
;     if ((++_sp & 255u) == 0u) { if (xb_ld(&(bar)[XB_TMO])) break; if (_sp > XB_SPIN_CAP) { atomicAdd(&(bar)[XB_TMO], 1u); break; } } } } while (0)
; __device__ __forceinline__ void xcd_barrier(unsigned* bar, volatile LAS unsigned* st, int wv0) {
;     ...
;         const unsigned old = xb_add(&bar[XB_XSUB(x)], 1u);
;         const unsigned gen = old / nloc;
;         if (old + 1u == (gen + 1u) * nloc) {
;             __builtin_amdgcn_fence(__ATOMIC_RELEASE, "agent");
;             asm volatile("s_waitcnt vmcnt(0)" ::: "memory");
;             const unsigned og = xb_add(&bar[XB_TOP], 1u);
;             const unsigned tg = og / nx;
;             if (og + 1u == (tg + 1u) * nx) xb_add(&bar[XB_TOPGEN], 1u);
;             else XB_SPIN(xb_ld(&bar[XB_TOPGEN]) == tg, bar);
;             __builtin_amdgcn_fence(__ATOMIC_ACQUIRE, "agent");
;             xb_add(&bar[XB_XGEN(x)], 1u);
;             asm volatile("s_waitcnt vmcnt(0)" ::: "memory");
;         } else {
;             XB_SPIN(xb_ld(&bar[XB_XGEN(x)]) == gen, bar);
.LBB0_629:
	s_lshl_b32 s92, s0, 8
	v_lshl_add_u64 v[2:3], v[0:1], 0, s[92:93]
	v_add_co_u32_e32 v8, vcc, 0x27741000, v2
	v_mov_b32_e32 v5, 1
	s_nop 0
	v_addc_co_u32_e32 v9, vcc, 0, v3, vcc
	global_atomic_add v5, v[8:9], v5, off offset:1024 sc0
	v_cvt_f32_u32_e32 v7, v6
	v_sub_u32_e32 v8, 0, v6
	s_mov_b64 s[0:1], 0x27740000
	v_lshl_add_u64 v[2:3], v[2:3], 0, s[0:1]
	v_rcp_iflag_f32_e32 v7, v7
	s_nop 0
	v_mul_f32_e32 v7, 0x4f7ffffe, v7
	v_cvt_u32_f32_e32 v7, v7
	v_mul_lo_u32 v8, v8, v7
	v_mul_hi_u32 v8, v7, v8
	v_add_u32_e32 v7, v7, v8
	s_waitcnt vmcnt(0)
	v_mul_hi_u32 v7, v5, v7
	v_mul_lo_u32 v9, v7, v6
	v_add_u32_e32 v8, 1, v5
	v_sub_u32_e32 v5, v5, v9
	v_add_u32_e32 v10, 1, v7
	v_cmp_ge_u32_e32 vcc, v5, v6
	v_sub_u32_e32 v9, v5, v6
	s_nop 0
	v_cndmask_b32_e32 v7, v7, v10, vcc
	v_cndmask_b32_e32 v5, v5, v9, vcc
	v_add_u32_e32 v9, 1, v7
	v_cmp_ge_u32_e32 vcc, v5, v6
	s_nop 1
	v_cndmask_b32_e32 v5, v7, v9, vcc
	v_mad_u64_u32 v[6:7], s[0:1], v6, v5, v[6:7]
	v_cmp_ne_u32_e32 vcc, v8, v6
	s_and_saveexec_b64 s[0:1], vcc
	s_xor_b64 s[2:3], exec, s[0:1]
	s_cbranch_execz .LBB0_642
	buffer_inv sc1
	v_add_co_u32_e32 v6, vcc, 0x2000, v2
	s_nop 1
	v_addc_co_u32_e32 v7, vcc, 0, v3, vcc
	s_waitcnt lgkmcnt(0)
	global_load_dword v4, v[6:7], off offset:1024 sc1
	s_waitcnt vmcnt(0)
	v_cmp_eq_u32_e32 vcc, v4, v5
	s_and_saveexec_b64 s[4:5], vcc
	s_cbranch_execz .LBB0_641
	s_mov_b64 s[0:1], 0x2400
	v_lshl_add_u64 v[2:3], v[2:3], 0, s[0:1]
	s_mov_b64 s[0:1], 0x27740200
	v_lshl_add_u64 v[0:1], v[0:1], 0, s[0:1]
	s_mov_b32 s0, 1
	s_mov_b64 s[6:7], 0
	s_branch .LBB0_633

; __device__ __forceinline__ unsigned xb_ld(unsigned* p)              { return __hip_atomic_load(p, __ATOMIC_RELAXED, __HIP_MEMORY_SCOPE_AGENT); }
; #define XB_SPIN(cond, bar) do { unsigned _sp = 0; while (cond) { __builtin_amdgcn_s_sleep(1); \
;     if ((++_sp & 255u) == 0u) { if (xb_ld(&(bar)[XB_TMO])) break; if (_sp > XB_SPIN_CAP) { atomicAdd(&(bar)[XB_TMO], 1u); break; } } } } while (0)
; __device__ __forceinline__ void xcd_barrier(unsigned* bar, volatile LAS unsigned* st, int wv0) {
;     ...
;             XB_SPIN(xb_ld(&bar[XB_XGEN(x)]) == gen, bar);
;             __builtin_amdgcn_fence(__ATOMIC_ACQUIRE, "agent");
;             asm volatile("s_waitcnt vmcnt(0)" ::: "memory");
.LBB0_641:
	s_or_b64 exec, exec, s[4:5]
	s_waitcnt vmcnt(0)
	s_waitcnt vmcnt(0)

; __device__ __forceinline__ unsigned xb_ld(unsigned* p)              { return __hip_atomic_load(p, __ATOMIC_RELAXED, __HIP_MEMORY_SCOPE_AGENT); }
; __device__ __forceinline__ unsigned xb_add(unsigned* p, unsigned v) { return __hip_atomic_fetch_add(p, v, __ATOMIC_RELAXED, __HIP_MEMORY_SCOPE_AGENT); }
; #define XB_SPIN(cond, bar) do { unsigned _sp = 0; while (cond) { __builtin_amdgcn_s_sleep(1); \
;     if ((++_sp & 255u) == 0u) { if (xb_ld(&(bar)[XB_TMO])) break; if (_sp > XB_SPIN_CAP) { atomicAdd(&(bar)[XB_TMO], 1u); break; } } } } while (0)
; __device__ __forceinline__ void xcd_barrier(unsigned* bar, volatile LAS unsigned* st, int wv0) {
;     ...
;         const unsigned old = xb_add(&bar[XB_XSUB(x)], 1u);
;         const unsigned gen = old / nloc;
;         if (old + 1u == (gen + 1u) * nloc) {
;             __builtin_amdgcn_fence(__ATOMIC_RELEASE, "agent");
;             asm volatile("s_waitcnt vmcnt(0)" ::: "memory");
;             const unsigned og = xb_add(&bar[XB_TOP], 1u);
;             const unsigned tg = og / nx;
;             if (og + 1u == (tg + 1u) * nx) xb_add(&bar[XB_TOPGEN], 1u);
;             else XB_SPIN(xb_ld(&bar[XB_TOPGEN]) == tg, bar);
;             __builtin_amdgcn_fence(__ATOMIC_ACQUIRE, "agent");
;             xb_add(&bar[XB_XGEN(x)], 1u);
;             asm volatile("s_waitcnt vmcnt(0)" ::: "memory");
;         } else {
;             XB_SPIN(xb_ld(&bar[XB_XGEN(x)]) == gen, bar);
.LBB0_785:
	s_or_b64 exec, exec, s[8:9]
	v_cvt_f32_u32_e32 v4, v2
	s_waitcnt vmcnt(0)
	v_readfirstlane_b32 s0, v3
	v_sub_u32_e32 v3, 0, v2
	v_rcp_iflag_f32_e32 v4, v4
	v_add_u32_e32 v5, s0, v1
	v_mul_f32_e32 v4, 0x4f7ffffe, v4
	v_cvt_u32_f32_e32 v4, v4
	v_mul_lo_u32 v1, v3, v4
	v_mul_hi_u32 v1, v4, v1
	v_add_u32_e32 v1, v4, v1
	v_mul_hi_u32 v1, v5, v1
	v_mul_lo_u32 v3, v1, v2
	v_sub_u32_e32 v3, v5, v3
	v_add_u32_e32 v4, 1, v1
	v_cmp_ge_u32_e32 vcc, v3, v2
	s_nop 1
	v_cndmask_b32_e32 v1, v1, v4, vcc
	v_sub_u32_e32 v4, v3, v2
	v_cndmask_b32_e32 v3, v3, v4, vcc
	v_add_u32_e32 v4, 1, v1
	v_cmp_ge_u32_e32 vcc, v3, v2
	v_add_u32_e32 v3, 1, v5
	s_nop 0
	v_cndmask_b32_e32 v1, v1, v4, vcc
	v_mul_lo_u32 v4, v2, v1
	v_add_u32_e32 v2, v4, v2
	v_cmp_ne_u32_e32 vcc, v3, v2
	s_and_saveexec_b64 s[0:1], vcc
	s_xor_b64 s[6:7], exec, s[0:1]
	s_cbranch_execz .LBB0_799
	buffer_inv sc1
	s_waitcnt lgkmcnt(0)
	global_load_dword v0, v231, s[4:5] offset:1024 sc1
	s_add_u32 s12, s4, 0x2400
	s_addc_u32 s13, s5, 0
	s_waitcnt vmcnt(0)
	v_cmp_eq_u32_e32 vcc, v0, v1
	s_and_saveexec_b64 s[8:9], vcc
	s_cbranch_execz .LBB0_798
	s_add_u32 s10, s86, 0x27740200
	s_addc_u32 s11, s87, 0
	s_mov_b32 s0, 1
	s_mov_b64 s[14:15], 0
	s_branch .LBB0_789

; __device__ __forceinline__ unsigned xb_ld(unsigned* p)              { return __hip_atomic_load(p, __ATOMIC_RELAXED, __HIP_MEMORY_SCOPE_AGENT); }
; __device__ __forceinline__ unsigned xb_add(unsigned* p, unsigned v) { return __hip_atomic_fetch_add(p, v, __ATOMIC_RELAXED, __HIP_MEMORY_SCOPE_AGENT); }
; #define XB_SPIN(cond, bar) do { unsigned _sp = 0; while (cond) { __builtin_amdgcn_s_sleep(1); \
;     if ((++_sp & 255u) == 0u) { if (xb_ld(&(bar)[XB_TMO])) break; if (_sp > XB_SPIN_CAP) { atomicAdd(&(bar)[XB_TMO], 1u); break; } } } } while (0)
; __device__ __forceinline__ void xcd_barrier(unsigned* bar, volatile LAS unsigned* st, int wv0) {
;     ...
;         const unsigned old = xb_add(&bar[XB_XSUB(x)], 1u);
;         const unsigned gen = old / nloc;
;         if (old + 1u == (gen + 1u) * nloc) {
;             __builtin_amdgcn_fence(__ATOMIC_RELEASE, "agent");
;             asm volatile("s_waitcnt vmcnt(0)" ::: "memory");
;             const unsigned og = xb_add(&bar[XB_TOP], 1u);
;             const unsigned tg = og / nx;
;             if (og + 1u == (tg + 1u) * nx) xb_add(&bar[XB_TOPGEN], 1u);
;             else XB_SPIN(xb_ld(&bar[XB_TOPGEN]) == tg, bar);
;             __builtin_amdgcn_fence(__ATOMIC_ACQUIRE, "agent");
;             xb_add(&bar[XB_XGEN(x)], 1u);
;             asm volatile("s_waitcnt vmcnt(0)" ::: "memory");
;         } else {
;             XB_SPIN(xb_ld(&bar[XB_XGEN(x)]) == gen, bar);
.LBB0_864:
	s_or_b64 exec, exec, s[10:11]
	v_cvt_f32_u32_e32 v4, v2
	s_waitcnt vmcnt(0)
	v_readfirstlane_b32 s0, v3
	v_sub_u32_e32 v3, 0, v2
	v_rcp_iflag_f32_e32 v4, v4
	v_add_u32_e32 v5, s0, v1
	v_mul_f32_e32 v4, 0x4f7ffffe, v4
	v_cvt_u32_f32_e32 v4, v4
	v_mul_lo_u32 v1, v3, v4
	v_mul_hi_u32 v1, v4, v1
	v_add_u32_e32 v1, v4, v1
	v_mul_hi_u32 v1, v5, v1
	v_mul_lo_u32 v3, v1, v2
	v_sub_u32_e32 v3, v5, v3
	v_add_u32_e32 v4, 1, v1
	v_cmp_ge_u32_e32 vcc, v3, v2
	s_nop 1
	v_cndmask_b32_e32 v1, v1, v4, vcc
	v_sub_u32_e32 v4, v3, v2
	v_cndmask_b32_e32 v3, v3, v4, vcc
	v_add_u32_e32 v4, 1, v1
	v_cmp_ge_u32_e32 vcc, v3, v2
	v_add_u32_e32 v3, 1, v5
	s_nop 0
	v_cndmask_b32_e32 v1, v1, v4, vcc
	v_mul_lo_u32 v4, v2, v1
	v_add_u32_e32 v2, v4, v2
	v_cmp_ne_u32_e32 vcc, v3, v2
	s_and_saveexec_b64 s[0:1], vcc
	s_xor_b64 s[8:9], exec, s[0:1]
	s_cbranch_execz .LBB0_878
	buffer_inv sc1
	s_waitcnt lgkmcnt(0)
	global_load_dword v0, v231, s[6:7] offset:1024 sc1
	s_add_u32 s14, s6, 0x2400
	s_addc_u32 s15, s7, 0
	s_waitcnt vmcnt(0)
	v_cmp_eq_u32_e32 vcc, v0, v1
	s_and_saveexec_b64 s[10:11], vcc
	s_cbranch_execz .LBB0_877
	s_add_u32 s12, s4, 0x27740200
	s_addc_u32 s13, s5, 0
	s_mov_b32 s0, 1
	s_mov_b64 s[16:17], 0
	s_branch .LBB0_868

; __device__ __forceinline__ unsigned xb_ld(unsigned* p)              { return __hip_atomic_load(p, __ATOMIC_RELAXED, __HIP_MEMORY_SCOPE_AGENT); }
; #define XB_SPIN(cond, bar) do { unsigned _sp = 0; while (cond) { __builtin_amdgcn_s_sleep(1); \
;     if ((++_sp & 255u) == 0u) { if (xb_ld(&(bar)[XB_TMO])) break; if (_sp > XB_SPIN_CAP) { atomicAdd(&(bar)[XB_TMO], 1u); break; } } } } while (0)
; __device__ __forceinline__ void xcd_barrier(unsigned* bar, volatile LAS unsigned* st, int wv0) {
;     ...
;             XB_SPIN(xb_ld(&bar[XB_XGEN(x)]) == gen, bar);
;             __builtin_amdgcn_fence(__ATOMIC_ACQUIRE, "agent");
;             asm volatile("s_waitcnt vmcnt(0)" ::: "memory");
.LBB0_877:
	s_or_b64 exec, exec, s[10:11]
	s_waitcnt vmcnt(0)
	s_waitcnt vmcnt(0)

; __device__ __forceinline__ unsigned xb_ld(unsigned* p)              { return __hip_atomic_load(p, __ATOMIC_RELAXED, __HIP_MEMORY_SCOPE_AGENT); }
; __device__ __forceinline__ unsigned xb_add(unsigned* p, unsigned v) { return __hip_atomic_fetch_add(p, v, __ATOMIC_RELAXED, __HIP_MEMORY_SCOPE_AGENT); }
; #define XB_SPIN(cond, bar) do { unsigned _sp = 0; while (cond) { __builtin_amdgcn_s_sleep(1); \
;     if ((++_sp & 255u) == 0u) { if (xb_ld(&(bar)[XB_TMO])) break; if (_sp > XB_SPIN_CAP) { atomicAdd(&(bar)[XB_TMO], 1u); break; } } } } while (0)
; __device__ __forceinline__ void xcd_barrier(unsigned* bar, volatile LAS unsigned* st, int wv0) {
;     ...
;         const unsigned old = xb_add(&bar[XB_XSUB(x)], 1u);
;         const unsigned gen = old / nloc;
;         if (old + 1u == (gen + 1u) * nloc) {
;             __builtin_amdgcn_fence(__ATOMIC_RELEASE, "agent");
;             asm volatile("s_waitcnt vmcnt(0)" ::: "memory");
;             const unsigned og = xb_add(&bar[XB_TOP], 1u);
;             const unsigned tg = og / nx;
;             if (og + 1u == (tg + 1u) * nx) xb_add(&bar[XB_TOPGEN], 1u);
;             else XB_SPIN(xb_ld(&bar[XB_TOPGEN]) == tg, bar);
;             __builtin_amdgcn_fence(__ATOMIC_ACQUIRE, "agent");
;             xb_add(&bar[XB_XGEN(x)], 1u);
;             asm volatile("s_waitcnt vmcnt(0)" ::: "memory");
;         } else {
;             XB_SPIN(xb_ld(&bar[XB_XGEN(x)]) == gen, bar);
.LBB0_1452:
	s_or_b64 exec, exec, s[10:11]
	v_cvt_f32_u32_e32 v4, v2
	s_waitcnt vmcnt(0)
	v_readfirstlane_b32 s0, v3
	v_sub_u32_e32 v3, 0, v2
	v_rcp_iflag_f32_e32 v4, v4
	v_add_u32_e32 v5, s0, v1
	v_mul_f32_e32 v4, 0x4f7ffffe, v4
	v_cvt_u32_f32_e32 v4, v4
	v_mul_lo_u32 v1, v3, v4
	v_mul_hi_u32 v1, v4, v1
	v_add_u32_e32 v1, v4, v1
	v_mul_hi_u32 v1, v5, v1
	v_mul_lo_u32 v3, v1, v2
	v_sub_u32_e32 v3, v5, v3
	v_add_u32_e32 v4, 1, v1
	v_cmp_ge_u32_e32 vcc, v3, v2
	s_nop 1
	v_cndmask_b32_e32 v1, v1, v4, vcc
	v_sub_u32_e32 v4, v3, v2
	v_cndmask_b32_e32 v3, v3, v4, vcc
	v_add_u32_e32 v4, 1, v1
	v_cmp_ge_u32_e32 vcc, v3, v2
	v_add_u32_e32 v3, 1, v5
	s_nop 0
	v_cndmask_b32_e32 v1, v1, v4, vcc
	v_mul_lo_u32 v4, v2, v1
	v_add_u32_e32 v2, v4, v2
	v_cmp_ne_u32_e32 vcc, v3, v2
	s_and_saveexec_b64 s[0:1], vcc
	s_xor_b64 s[6:7], exec, s[0:1]
	s_cbranch_execz .LBB0_1466
	buffer_inv sc1
	s_waitcnt lgkmcnt(0)
	global_load_dword v0, v231, s[4:5] offset:1024 sc1
	s_add_u32 s14, s4, 0x2400
	s_addc_u32 s15, s5, 0
	s_waitcnt vmcnt(0)
	v_cmp_eq_u32_e32 vcc, v0, v1
	s_and_saveexec_b64 s[10:11], vcc
	s_cbranch_execz .LBB0_1465
	s_add_u32 s12, s8, 0x27740200
	s_addc_u32 s13, s9, 0
	s_mov_b32 s0, 1
	s_mov_b64 s[16:17], 0
	s_branch .LBB0_1456
